# strategy: one static priority raise (s_setprio 1) for the younger half, waves 4-7, during attention units; reset at queue-loop head
# speedup vs baseline: 1.0060x; 1.0060x over previous
; __device__ __forceinline__ void attn_unit2f(unsigned char* ws, LAS unsigned char* lds, int s, int kvh, int qb, int hp, int tid, int wave, int lane) {
;     const int L = seq_L(s), Lp = seq_Lpad(s), ntile = Lp >> 7;
;     const int h0 = kvh * 4 + hp * 2;
;     const GAS bf16_t* Q = (const GAS bf16_t*)(ws + OFF_Q);
;     const GAS bf16_t* Kg = (const GAS bf16_t*)(ws + OFF_KP) + ((size_t)seq_koff(s) * 4 + (size_t)kvh * Lp) * 64;
;     const GAS bf16_t* Vg = (const GAS bf16_t*)(ws + OFF_VT) + (size_t)seq_koff(s) * 4 * 64 + (size_t)kvh * 64 * Lp;
;     GAS bf16_t* O = (GAS bf16_t*)(ws + OFF_B);
;     const int l31 = lane & 31, hi = lane >> 5, row = seq_base(s) + qb * 256 + wave * 32 + l31;
;     bf16x8 qf[2][4];
; #pragma unroll
;     for (int nh = 0; nh < 2; ++nh)
; #pragma unroll
;         for (int kk = 0; kk < 4; ++kk) qf[nh][kk] = *(const GAS bf16x8*)(Q + (size_t)row * 1024 + (h0 + nh) * 64 + 16 * kk + 8 * hi);
;     LAS bf16_t* Ks = (LAS bf16_t*)lds;
; __global__ void __launch_bounds__(512, 2) fwd_kernel(Params p) {
;     ...
;                 for (;;) {
;                     unsigned char* wsl = ws; asm volatile("" : "+s"(wsl)); wsl = (unsigned char*)(GAS unsigned char*)wsl;
;                     int tidl = tid; asm volatile("" : "+v"(tidl)); const int lanel = tidl & 63;
;                     if (tidl == 0) MISC[0] = (int)atomicAdd((unsigned*)(wsl + OFF_CTL) + 3, 1u);
;                     __syncthreads();
;                     const int u = __builtin_amdgcn_readfirstlane(MISC[0]);
;                     __syncthreads();
;                     if (u >= Q4) break;
;                     asm volatile("" : "+s"(fast_i));
;                     if (u < Q1) { if (fast_i) attn_unit2f(wsl, lds, 0, u >> 7, (u & 127) >> 1, u & 1, tidl, wave, lanel); else attn_unit2(wsl, lds, 0, u >> 7, (u & 127) >> 1, u & 1, tidl, wave, lanel, 0); }
;                     else if (u < Q3) { const int j = u - Q1, jj = j >> 1; const int cgl = jj < 128 ? 1 + jj : 129 + 17 * ((jj - 128) >> 4) + 1 + ((jj - 128) & 15);
;                         ssd_out_unit(p, lds, cgl * 2 + (j & 1), tidl, wave, lanel); }
;                     else { const int v = u - Q3; if (fast_i) attn_unit2f(wsl, lds, 1 + (v >> 6), (v >> 4) & 3, (v >> 1) & 7, v & 1, tidl, wave, lanel); else attn_unit2(wsl, lds, 1 + (v >> 6), (v >> 4) & 3, (v >> 1) & 7, v & 1, tidl, wave, lanel, 0); }
.LBB0_1155:
	s_setprio 0
	s_mov_b64 s[78:79], s[72:73]
	v_mov_b32_e32 v235, v225
	s_nop 0
	v_cmp_eq_u32_e32 vcc, 0, v235
	s_and_saveexec_b64 s[0:1], vcc
	s_cbranch_execz .LBB0_1157
	v_mov_b32_e32 v0, s78
	v_add_co_u32_e32 v0, vcc, 0x9d80000, v0
	v_mov_b32_e32 v1, s79
	s_nop 0
	v_addc_co_u32_e32 v1, vcc, 0, v1, vcc
	flat_atomic_add v0, v[0:1], v232 offset:12 sc0
	v_readlane_b32 s4, v255, 0
	s_nop 1
	v_mov_b32_e32 v1, s4
	s_waitcnt vmcnt(0) lgkmcnt(0)
	ds_write_b32 v1, v0
.LBB0_1157:
	s_or_b64 exec, exec, s[0:1]
	s_waitcnt lgkmcnt(0)
	s_barrier
	ds_read_b32 v0, v234
	s_waitcnt lgkmcnt(0)
	s_barrier
	v_readfirstlane_b32 s4, v0
	s_cmpk_gt_i32 s4, 0x5ff
	s_cselect_b64 s[0:1], -1, 0
	s_and_b64 vcc, exec, s[0:1]
	s_cbranch_vccnz .LBB0_1154
	v_writelane_b32 v255, s0, 5
	v_and_b32_e32 v236, 63, v235
	s_cmpk_gt_i32 s4, 0x1ff
	v_writelane_b32 v255, s1, 6
	v_readlane_b32 s0, v254, 29
	v_writelane_b32 v255, s4, 7
	s_nop 0
	v_writelane_b32 v254, s0, 29
	s_mov_b64 s[0:1], -1
	s_cbranch_scc0 .LBB0_1435
	v_readlane_b32 s0, v255, 7
	s_cmpk_gt_u32 s0, 0x3ff
	s_mov_b64 s[0:1], -1
	s_cbranch_scc0 .LBB0_1186
	v_readlane_b32 s6, v252, 48
	s_cmp_lt_u32 s6, 4
	s_cbranch_scc1 .Lprio_small_skip
	s_setprio 1
.Lprio_small_skip:
	v_readlane_b32 s6, v255, 7
	s_add_i32 s0, s6, 0xfffffc00
	s_bfe_u32 s4, s6, 0x20004
	s_lshl_b32 s9, s6, 7
	s_lshr_b32 s0, s0, 6
	s_lshl_b32 s5, s4, 8
	s_and_b32 s6, s9, 0x80
	s_lshl_b32 s1, s0, 11
	s_or_b32 s21, s5, s6
	s_add_u32 s6, s78, 0x205b1d00
	s_mul_i32 s0, s0, 0x110000
	s_addc_u32 s7, s79, 0
	s_add_i32 s76, s0, 0x810000
	s_mul_i32 s8, s4, 0x44000
	s_add_u32 s4, s78, 0x21641d00
	s_addc_u32 s5, s79, 0
	s_and_b32 s0, s9, 0x700
	s_or_b32 s0, s1, s0
	s_add_i32 s1, s0, 0x800
	s_lshl_b32 s0, s21, 1
	s_add_u32 s9, s6, s76
	s_addc_u32 s21, s7, 0
	s_add_u32 s24, s9, s8
	s_addc_u32 s25, s21, 0
	s_add_u32 s9, s4, s76
	s_addc_u32 s21, s5, 0
	s_add_u32 s26, s9, s8
	v_and_b32_e32 v240, 31, v235
	v_readlane_b32 s9, v254, 30
	v_lshrrev_b32_e32 v241, 5, v236
	v_lshlrev_b32_e32 v194, 4, v241
	v_or_b32_e32 v0, s9, v240
	v_add_u32_e32 v196, s1, v0
	v_ashrrev_i32_e32 v197, 31, v196
	v_lshlrev_b64 v[0:1], 11, v[196:197]
	v_lshl_add_u64 v[0:1], s[78:79], 0, v[0:1]
	v_lshl_add_u64 v[0:1], v[0:1], 0, v[194:195]
	s_mov_b32 s1, s77
	v_lshl_add_u64 v[0:1], v[0:1], 0, s[0:1]
	s_mov_b32 s1, 0x123f1000
	v_ashrrev_i32_e32 v6, 3, v235
	s_mov_b64 s[34:35], 0x123f1d00
	v_add_co_u32_e32 v4, vcc, s1, v0
	v_ashrrev_i32_e32 v7, 31, v6
	v_lshl_add_u64 v[2:3], v[0:1], 0, s[34:35]
	v_addc_co_u32_e32 v5, vcc, 0, v1, vcc
	v_lshlrev_b64 v[0:1], 7, v[6:7]
	v_lshlrev_b32_e32 v7, 4, v235
	v_lshl_add_u64 v[8:9], s[24:25], 0, v[0:1]
	v_and_b32_e32 v194, 0x70, v7
	global_load_dwordx4 v[128:131], v[2:3], off offset:64
	global_load_dwordx4 v[132:135], v[2:3], off offset:96
	v_lshl_add_u64 v[198:199], v[8:9], 0, v[194:195]
	global_load_dwordx4 v[136:139], v[2:3], off offset:32
	global_load_dwordx4 v[148:151], v[198:199], off
	s_addc_u32 s27, s21, 0
	v_mov_b64_e32 v[8:9], s[26:27]
	s_movk_i32 s1, 0x1100
	s_movk_i32 s9, 0x2000
	v_mad_i64_i32 v[8:9], s[24:25], v6, s1, v[8:9]
	v_add_co_u32_e32 v10, vcc, s9, v198
	v_lshl_add_u64 v[8:9], v[8:9], 0, v[194:195]
	s_nop 0
	v_addc_co_u32_e32 v11, vcc, 0, v199, vcc
	global_load_dwordx4 v[140:143], v[4:5], off offset:3328
	global_load_dwordx4 v[168:171], v[8:9], off
	global_load_dwordx4 v[164:167], v[10:11], off
	global_load_dwordx4 v[172:175], v[8:9], off offset:128
	global_load_dwordx4 v[144:147], v[2:3], off offset:128
	global_load_dwordx4 v[152:155], v[2:3], off offset:160
	global_load_dwordx4 v[156:159], v[2:3], off offset:192
	global_load_dwordx4 v[160:163], v[2:3], off offset:224
	v_mad_i64_i32 v[2:3], s[24:25], v6, s1, 0
	s_movk_i32 s1, 0x90
	s_mov_b32 s9, s77
	v_mul_lo_u32 v4, v6, s1
	v_mul_lo_u32 v5, v6, s30
	v_readlane_b32 s1, v254, 29
	v_lshlrev_b32_e32 v242, 3, v241
	v_lshlrev_b32_e32 v237, 2, v241
	v_lshlrev_b32_e32 v243, 7, v240
	v_add3_u32 v238, 0, v4, v194
	v_add3_u32 v239, 0, v5, v194
	s_cmp_eq_u32 s1, 0
	v_lshl_add_u64 v[200:201], s[8:9], 0, v[2:3]
	s_waitcnt vmcnt(8)
	ds_write_b128 v238, v[148:151]
	s_waitcnt vmcnt(5)
	ds_write_b128 v238, v[164:167] offset:9216
	ds_write_b128 v239, v[168:171] offset:36864
	s_waitcnt vmcnt(4)
	ds_write_b128 v239, v[172:175] offset:36992
	s_waitcnt lgkmcnt(0)
	s_cbranch_scc1 .LBB0_1164
	v_mad_u32_u24 v2, v240, s30, 0
	v_lshl_add_u32 v244, v241, 3, v2
	v_sub_u32_e32 v2, v2, v243
	v_lshl_add_u32 v245, v242, 1, v2
	v_and_b32_e32 v2, 7, v235
	v_lshl_add_u64 v[0:1], s[8:9], 0, v[0:1]
	v_lshlrev_b32_e32 v194, 4, v2
	v_lshl_add_u64 v[0:1], v[0:1], 0, v[194:195]
	v_lshl_add_u64 v[202:203], s[6:7], 0, v[0:1]
	v_lshl_add_u64 v[0:1], v[200:201], 0, v[194:195]
	v_lshl_add_u64 v[204:205], s[4:5], 0, v[0:1]
	v_mov_b32_e32 v0, 0
	s_mov_b32 s1, 0
	v_mov_b32_e32 v1, v0
	v_mov_b32_e32 v2, v0
	v_mov_b32_e32 v3, v0
	v_mov_b32_e32 v4, v0
	v_mov_b32_e32 v5, v0
	v_mov_b32_e32 v6, v0
	v_mov_b32_e32 v7, v0
	v_mov_b32_e32 v8, v0
	v_mov_b32_e32 v9, v0
	v_mov_b32_e32 v10, v0
	v_mov_b32_e32 v11, v0
	v_mov_b32_e32 v12, v0
	v_mov_b32_e32 v13, v0
	v_mov_b32_e32 v14, v0
	v_mov_b32_e32 v15, v0
	v_mov_b32_e32 v16, v0
	v_mov_b32_e32 v17, v0
	v_mov_b32_e32 v18, v0
	v_mov_b32_e32 v19, v0
	v_mov_b32_e32 v20, v0
	v_mov_b32_e32 v21, v0
	v_mov_b32_e32 v22, v0
	v_mov_b32_e32 v23, v0
	v_mov_b32_e32 v24, v0
	v_mov_b32_e32 v25, v0
	v_mov_b32_e32 v26, v0
	v_mov_b32_e32 v27, v0
	v_mov_b32_e32 v28, v0
	v_mov_b32_e32 v29, v0
	v_mov_b32_e32 v30, v0
	v_mov_b32_e32 v31, v0
	v_mov_b32_e32 v32, v0
	v_mov_b32_e32 v33, v0
	v_mov_b32_e32 v34, v0
	v_mov_b32_e32 v35, v0
	v_mov_b32_e32 v36, v0
	v_mov_b32_e32 v37, v0
	v_mov_b32_e32 v38, v0
	v_mov_b32_e32 v39, v0
	v_mov_b32_e32 v40, v0
	v_mov_b32_e32 v41, v0
	v_mov_b32_e32 v42, v0
	v_mov_b32_e32 v43, v0
	v_mov_b32_e32 v44, v0
	v_mov_b32_e32 v45, v0
	v_mov_b32_e32 v46, v0
	v_mov_b32_e32 v47, v0
	v_mov_b32_e32 v48, v0
	v_mov_b32_e32 v49, v0
	v_mov_b32_e32 v50, v0
	v_mov_b32_e32 v51, v0
	v_mov_b32_e32 v52, v0
	v_mov_b32_e32 v53, v0
	v_mov_b32_e32 v54, v0
	v_mov_b32_e32 v55, v0
	v_mov_b32_e32 v56, v0
	v_mov_b32_e32 v57, v0
	v_mov_b32_e32 v58, v0
	v_mov_b32_e32 v59, v0
	v_mov_b32_e32 v60, v0
	v_mov_b32_e32 v61, v0
	v_mov_b32_e32 v62, v0
	v_mov_b32_e32 v63, v0
	v_mov_b32_e32 v206, v0
	v_mov_b32_e32 v207, v0
	s_barrier

; #define LAS __attribute__((address_space(3)))
; #define GAS __attribute__((address_space(1)))
; __device__ __forceinline__ void attn_unit2f(unsigned char* ws, LAS unsigned char* lds, int s, int kvh, int qb, int hp, int tid, int wave, int lane) {
;     const int L = seq_L(s), Lp = seq_Lpad(s), ntile = Lp >> 7;
;     const int h0 = kvh * 4 + hp * 2;
;     const GAS bf16_t* Q = (const GAS bf16_t*)(ws + OFF_Q);
;     const GAS bf16_t* Kg = (const GAS bf16_t*)(ws + OFF_KP) + ((size_t)seq_koff(s) * 4 + (size_t)kvh * Lp) * 64;
;     const GAS bf16_t* Vg = (const GAS bf16_t*)(ws + OFF_VT) + (size_t)seq_koff(s) * 4 * 64 + (size_t)kvh * 64 * Lp;
;     GAS bf16_t* O = (GAS bf16_t*)(ws + OFF_B);
;     const int l31 = lane & 31, hi = lane >> 5, row = seq_base(s) + qb * 256 + wave * 32 + l31;
;     bf16x8 qf[2][4];
; #pragma unroll
;     for (int nh = 0; nh < 2; ++nh)
; #pragma unroll
;         for (int kk = 0; kk < 4; ++kk) qf[nh][kk] = *(const GAS bf16x8*)(Q + (size_t)row * 1024 + (h0 + nh) * 64 + 16 * kk + 8 * hi);
;     LAS bf16_t* Ks = (LAS bf16_t*)lds;
;     LAS bf16_t* Vs = (LAS bf16_t*)(lds + 2 * 128 * KPITCH * 2);
;     const int sr = tid >> 3, sc = (tid & 7) * 8;
;     const GAS bf16_t* kgp = Kg + (size_t)sr * 64 + sc;
;     const GAS bf16_t* vgp = Vg + (size_t)sr * Lp + sc;
;     u32x4 kreg0 = *(const GAS u32x4*)kgp, kreg1 = *(const GAS u32x4*)(kgp + 64 * 64), vreg0 = *(const GAS u32x4*)vgp, vreg1 = *(const GAS u32x4*)(vgp + 64);
;     *(LAS u32x4*)(Ks + sr * KPITCH + sc) = kreg0; *(LAS u32x4*)(Ks + (sr + 64) * KPITCH + sc) = kreg1;
;     *(LAS u32x4*)(Vs + sr * VPITCH + sc) = vreg0; *(LAS u32x4*)(Vs + sr * VPITCH + sc + 64) = vreg1;
;     __syncthreads();
;     f32x16 Oa0, Oa1, Ob0, Ob1;
; #pragma unroll
;     for (int i = 0; i < 16; ++i) { Oa0[i] = 0.f; Oa1[i] = 0.f; Ob0[i] = 0.f; Ob1[i] = 0.f; }
; __global__ void __launch_bounds__(512, 2) fwd_kernel(Params p) {
;     ...
;                     if (u < Q1) { if (fast_i) attn_unit2f(wsl, lds, 0, u >> 7, (u & 127) >> 1, u & 1, tidl, wave, lanel); else attn_unit2(wsl, lds, 0, u >> 7, (u & 127) >> 1, u & 1, tidl, wave, lanel, 0); }
.LBB0_1435:
	s_andn2_b64 vcc, exec, s[0:1]
	s_cbranch_vccnz .LBB0_1153
	v_readlane_b32 s4, v252, 48
	s_cmp_lt_u32 s4, 4
	s_cbranch_scc1 .Lprio_big_skip
	s_setprio 1
.Lprio_big_skip:
	v_readlane_b32 s4, v255, 7
	s_ashr_i32 s1, s4, 7
	s_lshl_b32 s8, s4, 7
	s_lshl_b32 s0, s1, 8
	s_and_b32 s4, s8, 0x80
	s_or_b32 s0, s4, s0
	s_add_u32 s4, s78, 0x21641d00
	s_mul_hi_i32 s7, s1, 0x204000
	s_mul_i32 s6, s1, 0x204000
	s_addc_u32 s5, s79, 0
	s_and_b32 s1, s8, 0x3f00
	s_add_i32 s21, s1, s74
	v_and_b32_e32 v239, 31, v235
	v_or_b32_e32 v196, s21, v239
	v_ashrrev_i32_e32 v197, 31, v196
	v_lshrrev_b32_e32 v240, 5, v236
	v_lshlrev_b64 v[0:1], 11, v[196:197]
	v_lshl_add_u64 v[0:1], s[78:79], 0, v[0:1]
	v_lshlrev_b32_e32 v194, 4, v240
	s_ashr_i32 s1, s0, 31
	v_lshl_add_u64 v[0:1], v[0:1], 0, v[194:195]
	v_lshl_add_u64 v[0:1], s[0:1], 1, v[0:1]
	s_mov_b64 s[26:27], 0x123f1d00
	s_mov_b32 s21, 0x123f1000
	v_lshl_add_u64 v[2:3], v[0:1], 0, s[26:27]
	v_add_co_u32_e32 v0, vcc, s21, v0
	v_ashrrev_i32_e32 v200, 3, v235
	s_add_u32 s8, s78, s6
	v_addc_co_u32_e32 v1, vcc, 0, v1, vcc
	v_ashrrev_i32_e32 v201, 31, v200
	s_addc_u32 s9, s79, s7
	global_load_dwordx4 v[128:131], v[0:1], off offset:3328
	global_load_dwordx4 v[132:135], v[2:3], off offset:32
	global_load_dwordx4 v[136:139], v[2:3], off offset:64
	global_load_dwordx4 v[140:143], v[2:3], off offset:96
	global_load_dwordx4 v[144:147], v[2:3], off offset:128
	global_load_dwordx4 v[148:151], v[2:3], off offset:160
	global_load_dwordx4 v[152:155], v[2:3], off offset:192
	global_load_dwordx4 v[156:159], v[2:3], off offset:224
	v_lshlrev_b64 v[0:1], 7, v[200:201]
	s_add_u32 s24, s4, s6
	v_lshl_add_u64 v[0:1], s[8:9], 0, v[0:1]
	s_mov_b64 s[8:9], 0x205b1d00
	s_addc_u32 s25, s5, s7
	v_lshl_add_u64 v[202:203], v[0:1], 0, s[8:9]
	v_lshlrev_b32_e32 v0, 4, v235
	v_and_b32_e32 v194, 0x70, v0
	v_mov_b64_e32 v[0:1], s[24:25]
	s_mov_b32 s8, 0x8100
	v_mad_i64_i32 v[204:205], s[8:9], v200, s8, v[0:1]
	v_lshl_add_u64 v[198:199], v[202:203], 0, v[194:195]
	s_movk_i32 s8, 0x2000
	v_add_co_u32_e32 v2, vcc, s8, v198
	v_lshl_add_u64 v[0:1], v[204:205], 0, v[194:195]
	s_nop 0
	v_addc_co_u32_e32 v3, vcc, 0, v199, vcc
	global_load_dwordx4 v[160:163], v[198:199], off
	global_load_dwordx4 v[164:167], v[2:3], off
	global_load_dwordx4 v[168:171], v[0:1], off
	global_load_dwordx4 v[172:175], v[0:1], off offset:128
	s_movk_i32 s8, 0x90
	v_mul_lo_u32 v0, v200, s8
	v_add3_u32 v237, 0, v0, v194
	v_mul_lo_u32 v0, v200, s30
	v_readlane_b32 s23, v254, 29
	v_add3_u32 v238, 0, v0, v194
	v_and_b32_e32 v0, 7, v235
	s_cmp_eq_u32 s23, 0
	v_lshlrev_b32_e32 v241, 3, v240
	v_lshlrev_b32_e32 v236, 2, v240
	v_lshlrev_b32_e32 v201, 7, v239
	v_lshlrev_b32_e32 v194, 4, v0
	s_waitcnt vmcnt(3)
	ds_write_b128 v237, v[160:163]
	s_waitcnt vmcnt(2)
	ds_write_b128 v237, v[164:167] offset:9216
	s_waitcnt vmcnt(1)
	ds_write_b128 v238, v[168:171] offset:36864
	s_waitcnt vmcnt(0)
	ds_write_b128 v238, v[172:175] offset:36992
	s_waitcnt lgkmcnt(0)
	s_cbranch_scc1 .LBB0_1440
	v_mad_u32_u24 v0, v239, s30, 0
	v_lshl_add_u32 v235, v240, 3, v0
	v_sub_u32_e32 v0, v0, v201
	v_lshl_add_u32 v242, v241, 1, v0
	v_mov_b32_e32 v0, 0
	s_mov_b32 s8, 0
	v_mov_b32_e32 v1, v0
	v_mov_b32_e32 v2, v0
	v_mov_b32_e32 v3, v0
	v_mov_b32_e32 v4, v0
	v_mov_b32_e32 v5, v0
	v_mov_b32_e32 v6, v0
	v_mov_b32_e32 v7, v0
	v_mov_b32_e32 v8, v0
	v_mov_b32_e32 v9, v0
	v_mov_b32_e32 v10, v0
	v_mov_b32_e32 v11, v0
	v_mov_b32_e32 v12, v0
	v_mov_b32_e32 v13, v0
	v_mov_b32_e32 v14, v0
	v_mov_b32_e32 v15, v0
	v_mov_b32_e32 v16, v0
	v_mov_b32_e32 v17, v0
	v_mov_b32_e32 v18, v0
	v_mov_b32_e32 v19, v0
	v_mov_b32_e32 v20, v0
	v_mov_b32_e32 v21, v0
	v_mov_b32_e32 v22, v0
	v_mov_b32_e32 v23, v0
	v_mov_b32_e32 v24, v0
	v_mov_b32_e32 v25, v0
	v_mov_b32_e32 v26, v0
	v_mov_b32_e32 v27, v0
	v_mov_b32_e32 v28, v0
	v_mov_b32_e32 v29, v0
	v_mov_b32_e32 v30, v0
	v_mov_b32_e32 v31, v0
	v_mov_b32_e32 v32, v0
	v_mov_b32_e32 v33, v0
	v_mov_b32_e32 v34, v0
	v_mov_b32_e32 v35, v0
	v_mov_b32_e32 v36, v0
	v_mov_b32_e32 v37, v0
	v_mov_b32_e32 v38, v0
	v_mov_b32_e32 v39, v0
	v_mov_b32_e32 v40, v0
	v_mov_b32_e32 v41, v0
	v_mov_b32_e32 v42, v0
	v_mov_b32_e32 v43, v0
	v_mov_b32_e32 v44, v0
	v_mov_b32_e32 v45, v0
	v_mov_b32_e32 v46, v0
	v_mov_b32_e32 v47, v0
	v_mov_b32_e32 v48, v0
	v_mov_b32_e32 v49, v0
	v_mov_b32_e32 v50, v0
	v_mov_b32_e32 v51, v0
	v_mov_b32_e32 v52, v0
	v_mov_b32_e32 v53, v0
	v_mov_b32_e32 v54, v0
	v_mov_b32_e32 v55, v0
	v_mov_b32_e32 v56, v0
	v_mov_b32_e32 v57, v0
	v_mov_b32_e32 v58, v0
	v_mov_b32_e32 v59, v0
	v_mov_b32_e32 v60, v0
	v_mov_b32_e32 v61, v0
	v_mov_b32_e32 v62, v0
	v_mov_b32_e32 v63, v0
	v_mov_b32_e32 v206, v0
	v_mov_b32_e32 v207, v0
	s_barrier
